# fox unit prologue: issue the four forget-gate loads together instead of four serial load-wait rounds
# baseline (speedup 1.0000x reference)
; #define GAS __attribute__((address_space(1)))
; template <int MODE> ...
;     ...
;     u32x4 kreg = *(const GAS u32x4*)(kg + (size_t)t_first * 64 * LDH), vreg = *(const GAS u32x4*)(vg + (size_t)t_first * 64 * LDH);
;     float cq = 0.f;
;     if (MODE == 0) {
;         float lf[4];
; #pragma unroll
;         for (int i = 0; i < 4; ++i) { const float x = FL[(rowbase + 4 * tid + i) * 8] + bfv; lf[i] = (fminf(x, 0.f) - __logf(1.f + __expf(-fabsf(x)))) * L2E; }
;         const float s1 = lf[0], s2 = s1 + lf[1], s3 = s2 + lf[2], s4 = s3 + lf[3];
;         float v = s4;
; #pragma unroll
;         for (int off = 1; off < 64; off <<= 1) { const float n = __shfl_up(v, off); if (lane >= off) v += n; }
;         if (lane == 63) wt[wid] = v;
;         __syncthreads();
.LBB0_811:
	v_readlane_b32 s2, v254, 8
	s_mul_i32 s0, s2, 0x2aab
	s_lshr_b32 s1, s0, 31
	s_lshr_b32 s0, s0, 16
	s_add_i32 s0, s0, s1
	s_mul_i32 s1, s0, 6
	s_sub_i32 s4, s2, s1
	s_sext_i32_i16 s1, s4
	s_bfe_i64 s[4:5], s[4:5], 0x100000
	s_lshl_b32 s2, s1, 6
	s_lshl_b64 s[4:5], s[4:5], 2
	v_readlane_b32 s1, v252, 58
	s_add_u32 s8, s1, s4
	v_readlane_b32 s1, v252, 59
	s_addc_u32 s9, s1, s5
	s_add_u32 s4, s23, s4
	v_readlane_b32 s1, v252, 55
	s_addc_u32 s5, s1, s5
	v_mov_b32_e32 v1, v230
	global_load_dword v19, v0, s[4:5]
	s_ashr_i32 s3, s2, 31
	v_readfirstlane_b32 s1, v1
	s_ashr_i32 s6, s1, 6
	s_bfe_i64 s[0:1], s[0:1], 0x100000
	s_lshl_b64 s[4:5], s[0:1], 11
	v_readlane_b32 s0, v252, 56
	v_ashrrev_i32_e32 v18, 3, v1
	v_readlane_b32 s1, v252, 57
	v_add_u32_e32 v4, s4, v18
	v_lshlrev_b32_e32 v12, 2, v1
	v_mov_b64_e32 v[2:3], s[0:1]
	s_movk_i32 s0, 0x1880
	v_mad_i64_i32 v[2:3], s[0:1], v4, s0, v[2:3]
	v_lshlrev_b32_e32 v4, 3, v1
	v_ashrrev_i32_e32 v13, 31, v12
	v_and_b32_e32 v4, 56, v4
	v_lshl_add_u64 v[14:15], s[4:5], 0, v[12:13]
	v_lshl_add_u64 v[2:3], s[2:3], 1, v[2:3]
	v_lshlrev_b32_e32 v10, 1, v4
	v_mov_b32_e32 v11, v0
	v_lshlrev_b64 v[14:15], 5, v[14:15]
	v_lshl_add_u64 v[98:99], v[2:3], 0, v[10:11]
	v_lshl_add_u64 v[16:17], s[8:9], 0, v[14:15]
	global_load_dwordx4 v[2:5], v[98:99], off offset:768
	global_load_dwordx4 v[6:9], v[98:99], off offset:1536
	global_load_dword v11, v[16:17], off
	global_load_dword v176, v[16:17], off offset:32
	global_load_dword v177, v[16:17], off offset:64
	global_load_dword v179, v[16:17], off offset:96
	s_mov_b32 s8, 0xbfb8aa3b
	s_mov_b32 s7, 0x800000
	s_mov_b32 s9, 0x3f317217
	s_mov_b32 s10, 0x7f800000
	v_mov_b32_e32 v21, 0x41b17218
	s_waitcnt vmcnt(0)
	v_add_f32_e32 v11, v19, v11
	v_min_f32_e32 v13, 0, v11
	v_mul_f32_e64 v11, |v11|, s8
	v_exp_f32_e32 v11, v11
	s_nop 0
	v_add_f32_e32 v11, 1.0, v11
	v_cmp_gt_f32_e32 vcc, s7, v11
	s_nop 1
	v_cndmask_b32_e64 v14, 0, 32, vcc
	v_ldexp_f32 v11, v11, v14
	v_log_f32_e32 v11, v11
	s_nop 0
	v_mul_f32_e32 v14, 0x3f317217, v11
	v_fma_f32 v14, v11, s9, -v14
	v_fmac_f32_e32 v14, 0x3377d1cf, v11
	v_fmac_f32_e32 v14, 0x3f317217, v11
	v_cmp_lt_f32_e64 s[0:1], |v11|, s10
	s_nop 1
	v_cndmask_b32_e64 v11, v11, v14, s[0:1]
	v_cndmask_b32_e32 v14, 0, v21, vcc
	v_sub_f32_e32 v11, v11, v14
	v_sub_f32_e32 v11, v13, v11
	v_mul_f32_e32 v14, 0x3fb8aa3b, v11
	v_add_f32_e32 v11, v19, v176
	v_min_f32_e32 v13, 0, v11
	v_mul_f32_e64 v11, |v11|, s8
	v_exp_f32_e32 v11, v11
	s_nop 0
	v_add_f32_e32 v11, 1.0, v11
	v_cmp_gt_f32_e32 vcc, s7, v11
	s_nop 1
	v_cndmask_b32_e64 v15, 0, 32, vcc
	v_ldexp_f32 v11, v11, v15
	v_log_f32_e32 v11, v11
	s_nop 0
	v_mul_f32_e32 v15, 0x3f317217, v11
	v_fma_f32 v15, v11, s9, -v15
	v_fmac_f32_e32 v15, 0x3377d1cf, v11
	v_fmac_f32_e32 v15, 0x3f317217, v11
	v_cmp_lt_f32_e64 s[0:1], |v11|, s10
	s_nop 1
	v_cndmask_b32_e64 v11, v11, v15, s[0:1]
	v_cndmask_b32_e32 v15, 0, v21, vcc
	v_sub_f32_e32 v11, v11, v15
	v_sub_f32_e32 v13, v13, v11
	v_add_f32_e32 v11, v19, v177
	v_min_f32_e32 v15, 0, v11
	v_mul_f32_e64 v11, |v11|, s8
	v_exp_f32_e32 v11, v11
	s_nop 0
	v_add_f32_e32 v11, 1.0, v11
	v_cmp_gt_f32_e32 vcc, s7, v11
	s_nop 1
	v_cndmask_b32_e64 v20, 0, 32, vcc
	v_ldexp_f32 v11, v11, v20
	v_log_f32_e32 v11, v11
	s_nop 0
	v_mul_f32_e32 v20, 0x3f317217, v11
	v_fma_f32 v20, v11, s9, -v20
	v_fmac_f32_e32 v20, 0x3377d1cf, v11
	v_fmac_f32_e32 v20, 0x3f317217, v11
	v_cmp_lt_f32_e64 s[0:1], |v11|, s10
	s_nop 1
	v_cndmask_b32_e64 v11, v11, v20, s[0:1]
	v_cndmask_b32_e32 v20, 0, v21, vcc
	v_sub_f32_e32 v11, v11, v20
	v_sub_f32_e32 v20, v15, v11
	v_add_f32_e32 v11, v19, v179
	v_min_f32_e32 v15, 0, v11
	v_mul_f32_e64 v11, |v11|, s8
	v_exp_f32_e32 v11, v11
	v_add_u32_e32 v19, -1, v224
	v_add_f32_e32 v11, 1.0, v11
	v_cmp_gt_f32_e32 vcc, s7, v11
	s_nop 1
	v_cndmask_b32_e64 v16, 0, 32, vcc
	v_ldexp_f32 v11, v11, v16
	v_log_f32_e32 v11, v11
	s_nop 0
	v_mul_f32_e32 v16, 0x3f317217, v11
	v_fma_f32 v16, v11, s9, -v16
	v_fmac_f32_e32 v16, 0x3377d1cf, v11
	v_fmac_f32_e32 v16, 0x3f317217, v11
	v_cmp_lt_f32_e64 s[0:1], |v11|, s10
	s_nop 1
	v_cndmask_b32_e64 v11, v11, v16, s[0:1]
	v_cndmask_b32_e32 v16, 0, v21, vcc
	v_sub_f32_e32 v11, v11, v16
	v_sub_f32_e32 v17, v15, v11
	v_fmamk_f32 v15, v13, 0x3fb8aa3b, v14
	v_and_b32_e32 v13, 64, v224
	v_cmp_lt_i32_e32 vcc, v19, v13
	v_fmamk_f32 v16, v20, 0x3fb8aa3b, v15
	v_fmamk_f32 v17, v17, 0x3fb8aa3b, v16
	v_cndmask_b32_e32 v19, v19, v224, vcc
	v_lshlrev_b32_e32 v19, 2, v19
	ds_bpermute_b32 v19, v19, v17
	v_and_b32_e32 v11, 63, v1
	v_cmp_eq_u32_e32 vcc, 0, v11
	v_add_u32_e32 v20, -2, v224
	s_waitcnt lgkmcnt(0)
	v_add_f32_e32 v19, v17, v19
	v_cndmask_b32_e32 v19, v19, v17, vcc
	v_cmp_lt_i32_e32 vcc, v20, v13
	s_nop 1
	v_cndmask_b32_e32 v20, v20, v224, vcc
	v_lshlrev_b32_e32 v20, 2, v20
	ds_bpermute_b32 v20, v20, v19
	v_cmp_gt_u32_e32 vcc, 2, v11
	s_waitcnt lgkmcnt(0)
	v_add_f32_e32 v20, v19, v20
	v_cndmask_b32_e32 v19, v20, v19, vcc
	v_add_u32_e32 v20, -4, v224
	v_cmp_lt_i32_e32 vcc, v20, v13
	s_nop 1
	v_cndmask_b32_e32 v20, v20, v224, vcc
	v_lshlrev_b32_e32 v20, 2, v20
	ds_bpermute_b32 v20, v20, v19
	v_cmp_gt_u32_e32 vcc, 4, v11
	s_waitcnt lgkmcnt(0)
	v_add_f32_e32 v20, v19, v20
	v_cndmask_b32_e32 v19, v20, v19, vcc
	v_add_u32_e32 v20, -8, v224
	v_cmp_lt_i32_e32 vcc, v20, v13
	s_nop 1
	v_cndmask_b32_e32 v20, v20, v224, vcc
	v_lshlrev_b32_e32 v20, 2, v20
	ds_bpermute_b32 v20, v20, v19
	v_cmp_gt_u32_e32 vcc, 8, v11
	s_waitcnt lgkmcnt(0)
	v_add_f32_e32 v20, v19, v20
	v_cndmask_b32_e32 v19, v20, v19, vcc
	v_add_u32_e32 v20, -16, v224
	v_cmp_lt_i32_e32 vcc, v20, v13
	s_nop 1
	v_cndmask_b32_e32 v20, v20, v224, vcc
	v_lshlrev_b32_e32 v20, 2, v20
	ds_bpermute_b32 v20, v20, v19
	v_cmp_gt_u32_e32 vcc, 16, v11
	s_waitcnt lgkmcnt(0)
	v_add_f32_e32 v20, v19, v20
	v_cndmask_b32_e32 v19, v20, v19, vcc
	v_subrev_u32_e32 v20, 32, v224
	v_cmp_lt_i32_e32 vcc, v20, v13
	s_nop 1
	v_cndmask_b32_e32 v20, v20, v224, vcc
	v_lshlrev_b32_e32 v20, 2, v20
	ds_bpermute_b32 v20, v20, v19
	v_cmp_eq_u32_e32 vcc, 63, v11
	s_waitcnt lgkmcnt(0)
	v_add_f32_e32 v20, v19, v20
	s_and_saveexec_b64 s[0:1], vcc
	s_lshl_b32 s7, s6, 2
	s_add_i32 s7, s7, 0
	v_mov_b32_e32 v21, s7
	ds_write_b32 v21, v20 offset:45056
	s_or_b64 exec, exec, s[0:1]
	s_cmp_lt_i32 s6, 1
	s_waitcnt lgkmcnt(0)
	s_barrier
	s_cbranch_scc1 .LBB0_860
	ds_read_b32 v21, v0 offset:45056
	s_waitcnt lgkmcnt(0)
	v_add_f32_e32 v21, 0, v21
	s_cmp_lt_i32 s6, 2
	s_cbranch_scc1 .LBB0_816
